# w_out GEMM: f32 residual loads run 7 steps ahead in the epilogue (rolling prefetch)
# baseline (speedup 1.0000x reference)
; __device__ __forceinline__ unsigned cvt_pk_bf16(float lo, float hi) { unsigned r; asm volatile("v_cvt_pk_bf16_f32 %0, %1, %2" : "=v"(r) : "v"(lo), "v"(hi)); return r; }
; __device__ __forceinline__ float bflo(unsigned w) { return __uint_as_float(w << 16); }
; __device__ __forceinline__ float bfhi(unsigned w) { return __uint_as_float(w & 0xffff0000u); }
;   __device__ __forceinline__ void operator()(const f32x4 (&acc)[2][2][4][2], const Unit& u, int wr, int wc, int fr, int fq) const {
;     const int rowt = u.pm * BM; const int b = rowt >> 11;
;     const int row0 = rowt + wr * 64 + fr, col0 = u.pn * BM + wc * 32 + 8 * fq;
;     f32x4 gv[2][2];
; #pragma unroll
;     for (int bj = 0; bj < 2; ++bj)
; #pragma unroll
;       for (int n = 0; n < 2; ++n) gv[bj][n] = *(const f32x4*)(gate + (size_t)b * NMOD6 + col0 + bj * HALF + 4 * n);
; #pragma unroll
;     for (int ai = 0; ai < 2; ++ai)
; #pragma unroll
;       for (int m = 0; m < 4; ++m) { const size_t ro = (size_t)(row0 + ai * HALF + m * 16) * DM + col0;
; #pragma unroll
;         for (int bj = 0; bj < 2; ++bj) { f32x4 x0, x1;
;           if constexpr (XIN_F32) { x0 = *(const f32x4*)((const float*)xin + ro + bj * HALF); x1 = *(const f32x4*)((const float*)xin + ro + bj * HALF + 4); }
;           else { const u32x4 w = *(const u32x4*)((const bf16_t*)xin + ro + bj * HALF);
;             x0 = (f32x4){bflo(w.x), bfhi(w.x), bflo(w.y), bfhi(w.y)}; x1 = (f32x4){bflo(w.z), bfhi(w.z), bflo(w.w), bfhi(w.w)}; }
;           const f32x4 v0 = x0 + gv[bj][0] * acc[ai][bj][m][0], v1 = x1 + gv[bj][1] * acc[ai][bj][m][1];
;           u32x4 o; o.x = cvt_pk_bf16(v0[0], v0[1]); o.y = cvt_pk_bf16(v0[2], v0[3]); o.z = cvt_pk_bf16(v1[0], v1[1]); o.w = cvt_pk_bf16(v1[2], v1[3]);
;           *(u32x4*)(xout + ro + bj * HALF) = o; } }
;   }
.LBB0_747:
	v_lshl_add_u32 v164, s38, 8, v166
	s_ashr_i32 s27, s38, 3
	v_lshl_or_b32 v162, s59, 8, v168
	v_ashrrev_i32_e32 v165, 31, v164
	s_mul_hi_i32 s31, s27, 0xc000
	s_mul_i32 s27, s27, 0xc000
	v_ashrrev_i32_e32 v163, 31, v162
	v_lshlrev_b64 v[128:129], 11, v[164:165]
	s_add_u32 s40, s51, s27
	v_lshl_add_u64 v[160:161], v[128:129], 0, v[162:163]
	s_addc_u32 s41, s52, s31
	v_lshl_add_u64 v[182:183], v[160:161], 2, s[6:7]
	v_lshl_add_u64 v[132:133], v[162:163], 2, s[40:41]
	s_nop 0
	global_load_dwordx4 v[140:143], v[132:133], off
	global_load_dwordx4 v[136:139], v[132:133], off offset:16
	s_nop 0
	v_lshl_add_u64 v[184:185], v[160:161], 1, s[28:29]
	global_load_dwordx4 v[128:131], v[132:133], off offset:528
	s_nop 0
	global_load_dwordx4 v[132:135], v[132:133], off offset:512
	s_andn2_b64 vcc, exec, s[4:5]
	s_mov_b64 s[4:5], -1
	v_mov_b32_e32 v246, 0x20000
	v_mov_b32_e32 v247, 0
	v_mov_b32_e32 v242, v182
	v_mov_b32_e32 v243, v183
	global_load_dwordx4 v[186:189], v[242:243], off
	global_load_dwordx4 v[190:193], v[242:243], off offset:16
	global_load_dwordx4 v[194:197], v[242:243], off offset:512
	global_load_dwordx4 v[198:201], v[242:243], off offset:528
	v_lshl_add_u64 v[242:243], v[242:243], 0, v[246:247]
	global_load_dwordx4 v[202:205], v[242:243], off
	global_load_dwordx4 v[206:209], v[242:243], off offset:16
	global_load_dwordx4 v[210:213], v[242:243], off offset:512
	global_load_dwordx4 v[214:217], v[242:243], off offset:528
	v_lshl_add_u64 v[242:243], v[242:243], 0, v[246:247]
	global_load_dwordx4 v[218:221], v[242:243], off
	global_load_dwordx4 v[222:225], v[242:243], off offset:16
	global_load_dwordx4 v[226:229], v[242:243], off offset:512
	global_load_dwordx4 v[230:233], v[242:243], off offset:528
	v_lshl_add_u64 v[242:243], v[242:243], 0, v[246:247]
	global_load_dwordx4 v[234:237], v[242:243], off
	global_load_dwordx4 v[238:241], v[242:243], off offset:16
	s_waitcnt vmcnt(12)
	v_pk_fma_f32 v[124:125], v[124:125], v[140:141], v[186:187]
	v_pk_fma_f32 v[126:127], v[126:127], v[142:143], v[188:189]
	v_pk_fma_f32 v[174:175], v[122:123], v[138:139], v[192:193]
	v_pk_fma_f32 v[122:123], v[120:121], v[136:137], v[190:191]
	v_cvt_pk_bf16_f32 v120, v124, v125
	v_cvt_pk_bf16_f32 v121, v126, v127
	s_nop 0
	v_cvt_pk_bf16_f32 v122, v122, v123
	v_cvt_pk_bf16_f32 v123, v174, v175
	global_store_dwordx4 v[184:185], v[120:123], off
	global_load_dwordx4 v[186:189], v[242:243], off offset:512
	global_load_dwordx4 v[190:193], v[242:243], off offset:528
	s_nop 0
	s_nop 0
	s_nop 0
	v_or_b32_e32 v174, 16, v164
	v_ashrrev_i32_e32 v175, 31, v174
	v_lshlrev_b64 v[174:175], 11, v[174:175]
	v_lshl_add_u64 v[174:175], v[174:175], 0, v[162:163]
	v_lshl_add_u64 v[176:177], v[174:175], 2, s[6:7]
	s_waitcnt vmcnt(13)
	v_pk_fma_f32 v[116:117], v[116:117], v[132:133], v[194:195]
	s_waitcnt vmcnt(13)
	v_pk_fma_f32 v[120:121], v[114:115], v[130:131], v[200:201]
	v_pk_fma_f32 v[114:115], v[112:113], v[128:129], v[198:199]
	v_pk_fma_f32 v[118:119], v[118:119], v[134:135], v[196:197]
	v_cvt_pk_bf16_f32 v112, v116, v117
	s_nop 0
	v_cvt_pk_bf16_f32 v113, v118, v119
	v_cvt_pk_bf16_f32 v114, v114, v115
	v_cvt_pk_bf16_f32 v115, v120, v121
	global_store_dwordx4 v[184:185], v[112:115], off offset:256
	v_lshl_add_u64 v[242:243], v[242:243], 0, v[246:247]
	v_lshl_add_u64 v[242:243], v[242:243], 0, v[246:247]
	v_lshl_add_u64 v[242:243], v[242:243], 0, v[246:247]
	v_lshl_add_u64 v[242:243], v[242:243], 0, v[246:247]
	v_lshl_add_u64 v[242:243], v[242:243], 0, v[246:247]
	global_load_dwordx4 v[194:197], v[242:243], off
	global_load_dwordx4 v[198:201], v[242:243], off offset:16
	s_nop 0
	s_nop 0
	s_nop 0
	v_lshl_add_u64 v[120:121], v[174:175], 1, s[28:29]
	s_waitcnt vmcnt(14)
	v_pk_fma_f32 v[108:109], v[108:109], v[140:141], v[202:203]
	s_waitcnt vmcnt(14)
	v_pk_fma_f32 v[112:113], v[106:107], v[138:139], v[208:209]
	v_pk_fma_f32 v[106:107], v[104:105], v[136:137], v[206:207]
	v_pk_fma_f32 v[110:111], v[110:111], v[142:143], v[204:205]
	v_cvt_pk_bf16_f32 v104, v108, v109
	s_nop 0
	v_cvt_pk_bf16_f32 v105, v110, v111
	v_cvt_pk_bf16_f32 v106, v106, v107
	v_cvt_pk_bf16_f32 v107, v112, v113
	global_store_dwordx4 v[120:121], v[104:107], off
	global_load_dwordx4 v[202:205], v[242:243], off offset:512
	global_load_dwordx4 v[206:209], v[242:243], off offset:528
	s_nop 0
	s_nop 0
	s_nop 0
	v_or_b32_e32 v112, 32, v164
	v_ashrrev_i32_e32 v113, 31, v112
	v_lshlrev_b64 v[112:113], 11, v[112:113]
	v_lshl_add_u64 v[112:113], v[112:113], 0, v[162:163]
	v_lshl_add_u64 v[114:115], v[112:113], 2, s[6:7]
	s_waitcnt vmcnt(15)
	v_pk_fma_f32 v[100:101], v[100:101], v[132:133], v[210:211]
	s_waitcnt vmcnt(15)
	v_pk_fma_f32 v[104:105], v[98:99], v[130:131], v[216:217]
	v_pk_fma_f32 v[98:99], v[96:97], v[128:129], v[214:215]
	v_pk_fma_f32 v[102:103], v[102:103], v[134:135], v[212:213]
	v_cvt_pk_bf16_f32 v96, v100, v101
	s_nop 0
	v_cvt_pk_bf16_f32 v97, v102, v103
	v_cvt_pk_bf16_f32 v98, v98, v99
	v_cvt_pk_bf16_f32 v99, v104, v105
	global_store_dwordx4 v[120:121], v[96:99], off offset:256
	v_lshl_add_u64 v[242:243], v[242:243], 0, v[246:247]
	global_load_dwordx4 v[210:213], v[242:243], off
	global_load_dwordx4 v[214:217], v[242:243], off offset:16
	s_nop 0
	s_nop 0
	s_nop 0
	v_lshl_add_u64 v[104:105], v[112:113], 1, s[28:29]
	s_waitcnt vmcnt(16)
	v_pk_fma_f32 v[92:93], v[92:93], v[140:141], v[218:219]
	s_waitcnt vmcnt(16)
; __device__ __forceinline__ unsigned cvt_pk_bf16(float lo, float hi) { unsigned r; asm volatile("v_cvt_pk_bf16_f32 %0, %1, %2" : "=v"(r) : "v"(lo), "v"(hi)); return r; }
; __device__ __forceinline__ float bflo(unsigned w) { return __uint_as_float(w << 16); }
; __device__ __forceinline__ float bfhi(unsigned w) { return __uint_as_float(w & 0xffff0000u); }
;   __device__ __forceinline__ void operator()(const f32x4 (&acc)[2][2][4][2], const Unit& u, int wr, int wc, int fr, int fq) const {
;     ...
;     for (int ai = 0; ai < 2; ++ai)
; #pragma unroll
;       for (int m = 0; m < 4; ++m) { const size_t ro = (size_t)(row0 + ai * HALF + m * 16) * DM + col0;
; #pragma unroll
;         for (int bj = 0; bj < 2; ++bj) { f32x4 x0, x1;
;           if constexpr (XIN_F32) { x0 = *(const f32x4*)((const float*)xin + ro + bj * HALF); x1 = *(const f32x4*)((const float*)xin + ro + bj * HALF + 4); }
;           else { const u32x4 w = *(const u32x4*)((const bf16_t*)xin + ro + bj * HALF);
;             x0 = (f32x4){bflo(w.x), bfhi(w.x), bflo(w.y), bfhi(w.y)}; x1 = (f32x4){bflo(w.z), bfhi(w.z), bflo(w.w), bfhi(w.w)}; }
;           const f32x4 v0 = x0 + gv[bj][0] * acc[ai][bj][m][0], v1 = x1 + gv[bj][1] * acc[ai][bj][m][1];
;           u32x4 o; o.x = cvt_pk_bf16(v0[0], v0[1]); o.y = cvt_pk_bf16(v0[2], v0[3]); o.z = cvt_pk_bf16(v1[0], v1[1]); o.w = cvt_pk_bf16(v1[2], v1[3]);
;           *(u32x4*)(xout + ro + bj * HALF) = o; } }
;   }
	v_pk_fma_f32 v[96:97], v[90:91], v[138:139], v[224:225]
	v_pk_fma_f32 v[90:91], v[88:89], v[136:137], v[222:223]
	v_pk_fma_f32 v[94:95], v[94:95], v[142:143], v[220:221]
	v_cvt_pk_bf16_f32 v88, v92, v93
	s_nop 0
	v_cvt_pk_bf16_f32 v89, v94, v95
	v_cvt_pk_bf16_f32 v90, v90, v91
	v_cvt_pk_bf16_f32 v91, v96, v97
	global_store_dwordx4 v[104:105], v[88:91], off
	global_load_dwordx4 v[218:221], v[242:243], off offset:512
	global_load_dwordx4 v[222:225], v[242:243], off offset:528
	s_nop 0
	s_nop 0
	s_nop 0
	v_or_b32_e32 v96, 48, v164
	v_ashrrev_i32_e32 v97, 31, v96
	v_lshlrev_b64 v[96:97], 11, v[96:97]
	v_lshl_add_u64 v[96:97], v[96:97], 0, v[162:163]
	v_lshl_add_u64 v[98:99], v[96:97], 2, s[6:7]
	s_waitcnt vmcnt(17)
	v_pk_fma_f32 v[84:85], v[84:85], v[132:133], v[226:227]
	s_waitcnt vmcnt(17)
	v_pk_fma_f32 v[88:89], v[82:83], v[130:131], v[232:233]
	v_pk_fma_f32 v[82:83], v[80:81], v[128:129], v[230:231]
	v_pk_fma_f32 v[86:87], v[86:87], v[134:135], v[228:229]
	v_cvt_pk_bf16_f32 v80, v84, v85
	s_nop 0
	v_cvt_pk_bf16_f32 v81, v86, v87
	v_cvt_pk_bf16_f32 v82, v82, v83
	v_cvt_pk_bf16_f32 v83, v88, v89
	global_store_dwordx4 v[104:105], v[80:83], off offset:256
	v_lshl_add_u64 v[242:243], v[242:243], 0, v[246:247]
	global_load_dwordx4 v[226:229], v[242:243], off
	global_load_dwordx4 v[230:233], v[242:243], off offset:16
	s_nop 0
	s_nop 0
	s_nop 0
	v_lshl_add_u64 v[88:89], v[96:97], 1, s[28:29]
	s_waitcnt vmcnt(18)
	v_pk_fma_f32 v[76:77], v[76:77], v[140:141], v[234:235]
	s_waitcnt vmcnt(18)
	v_pk_fma_f32 v[80:81], v[74:75], v[138:139], v[240:241]
	v_pk_fma_f32 v[74:75], v[72:73], v[136:137], v[238:239]
	v_pk_fma_f32 v[78:79], v[78:79], v[142:143], v[236:237]
	v_cvt_pk_bf16_f32 v72, v76, v77
	s_nop 0
	v_cvt_pk_bf16_f32 v73, v78, v79
	v_cvt_pk_bf16_f32 v74, v74, v75
	v_cvt_pk_bf16_f32 v75, v80, v81
	global_store_dwordx4 v[88:89], v[72:75], off
	global_load_dwordx4 v[234:237], v[242:243], off offset:512
	global_load_dwordx4 v[238:241], v[242:243], off offset:528
	s_nop 0
	s_nop 0
	s_nop 0
	v_lshl_add_u64 v[80:81], v[160:161], 0, s[18:19]
	v_lshl_add_u64 v[82:83], v[80:81], 2, s[6:7]
	s_waitcnt vmcnt(18)
	v_pk_fma_f32 v[68:69], v[68:69], v[132:133], v[186:187]
	s_waitcnt vmcnt(18)
	v_pk_fma_f32 v[72:73], v[66:67], v[130:131], v[192:193]
	v_pk_fma_f32 v[66:67], v[64:65], v[128:129], v[190:191]
	v_pk_fma_f32 v[70:71], v[70:71], v[134:135], v[188:189]
	v_cvt_pk_bf16_f32 v64, v68, v69
	s_nop 0
	v_cvt_pk_bf16_f32 v65, v70, v71
	v_cvt_pk_bf16_f32 v66, v66, v67
	v_cvt_pk_bf16_f32 v67, v72, v73
	global_store_dwordx4 v[88:89], v[64:67], off offset:256
	v_lshl_add_u64 v[242:243], v[242:243], 0, v[246:247]
	global_load_dwordx4 v[186:189], v[242:243], off
	global_load_dwordx4 v[190:193], v[242:243], off offset:16
	s_nop 0
	s_nop 0
	s_nop 0
	v_lshl_add_u64 v[72:73], v[80:81], 1, s[28:29]
	s_waitcnt vmcnt(18)
	v_pk_fma_f32 v[60:61], v[60:61], v[140:141], v[194:195]
	s_waitcnt vmcnt(18)
	v_pk_fma_f32 v[64:65], v[58:59], v[138:139], v[200:201]
	v_pk_fma_f32 v[58:59], v[56:57], v[136:137], v[198:199]
	v_pk_fma_f32 v[62:63], v[62:63], v[142:143], v[196:197]
	v_cvt_pk_bf16_f32 v56, v60, v61
	s_nop 0
	v_cvt_pk_bf16_f32 v57, v62, v63
	v_cvt_pk_bf16_f32 v58, v58, v59
	v_cvt_pk_bf16_f32 v59, v64, v65
	global_store_dwordx4 v[72:73], v[56:59], off
	global_load_dwordx4 v[194:197], v[242:243], off offset:512
	global_load_dwordx4 v[198:201], v[242:243], off offset:528
	s_nop 0
	s_nop 0
	s_nop 0
	v_lshl_add_u64 v[64:65], v[160:161], 0, s[20:21]
	v_lshl_add_u64 v[66:67], v[64:65], 2, s[6:7]
	s_waitcnt vmcnt(18)
	v_pk_fma_f32 v[52:53], v[52:53], v[132:133], v[202:203]
	s_waitcnt vmcnt(18)
; __device__ __forceinline__ unsigned cvt_pk_bf16(float lo, float hi) { unsigned r; asm volatile("v_cvt_pk_bf16_f32 %0, %1, %2" : "=v"(r) : "v"(lo), "v"(hi)); return r; }
; __device__ __forceinline__ float bflo(unsigned w) { return __uint_as_float(w << 16); }
; __device__ __forceinline__ float bfhi(unsigned w) { return __uint_as_float(w & 0xffff0000u); }
; #define PG8_BAR __builtin_amdgcn_s_barrier()
; template <class Epi, class Sched, bool ALIGN_EPI = true>
; __device__ __forceinline__ void gemm_phase(LAS unsigned char* lds, const Gemm g, const Sched& S, const Epi& E) {
;     ...
;     if (!has_next) break;
; #pragma unroll
;     for (int a = 0; a < 2; ++a)
; #pragma unroll
;       for (int b = 0; b < 2; ++b)
; #pragma unroll
;         for (int m = 0; m < 4; ++m)
; #pragma unroll
;           for (int n = 0; n < 2; ++n) acc[a][b][m][n] = (f32x4){0.f, 0.f, 0.f, 0.f};
;     cur = nxt; cA = nA; cB = nB; kstep = kstepN; ++ui;
;     if constexpr (ALIGN_EPI) { if (wr == 1) PG8_BAR; }
;   __device__ __forceinline__ void operator()(const f32x4 (&acc)[2][2][4][2], const Unit& u, int wr, int wc, int fr, int fq) const {
;     ...
;       for (int m = 0; m < 4; ++m) { const size_t ro = (size_t)(row0 + ai * HALF + m * 16) * DM + col0;
; #pragma unroll
;         for (int bj = 0; bj < 2; ++bj) { f32x4 x0, x1;
;           if constexpr (XIN_F32) { x0 = *(const f32x4*)((const float*)xin + ro + bj * HALF); x1 = *(const f32x4*)((const float*)xin + ro + bj * HALF + 4); }
;           else { const u32x4 w = *(const u32x4*)((const bf16_t*)xin + ro + bj * HALF);
;             x0 = (f32x4){bflo(w.x), bfhi(w.x), bflo(w.y), bfhi(w.y)}; x1 = (f32x4){bflo(w.z), bfhi(w.z), bflo(w.w), bfhi(w.w)}; }
;           const f32x4 v0 = x0 + gv[bj][0] * acc[ai][bj][m][0], v1 = x1 + gv[bj][1] * acc[ai][bj][m][1];
;           u32x4 o; o.x = cvt_pk_bf16(v0[0], v0[1]); o.y = cvt_pk_bf16(v0[2], v0[3]); o.z = cvt_pk_bf16(v1[0], v1[1]); o.w = cvt_pk_bf16(v1[2], v1[3]);
;           *(u32x4*)(xout + ro + bj * HALF) = o; } }
	v_pk_fma_f32 v[56:57], v[50:51], v[130:131], v[208:209]
	v_pk_fma_f32 v[50:51], v[48:49], v[128:129], v[206:207]
	v_pk_fma_f32 v[54:55], v[54:55], v[134:135], v[204:205]
	v_cvt_pk_bf16_f32 v48, v52, v53
	s_nop 0
	v_cvt_pk_bf16_f32 v49, v54, v55
	v_cvt_pk_bf16_f32 v50, v50, v51
	v_cvt_pk_bf16_f32 v51, v56, v57
	global_store_dwordx4 v[72:73], v[48:51], off offset:256
	s_nop 0
	s_nop 0
	s_nop 0
	v_lshl_add_u64 v[56:57], v[64:65], 1, s[28:29]
	s_waitcnt vmcnt(16)
	v_pk_fma_f32 v[44:45], v[44:45], v[140:141], v[210:211]
	s_waitcnt vmcnt(16)
	v_pk_fma_f32 v[48:49], v[42:43], v[138:139], v[216:217]
	v_pk_fma_f32 v[42:43], v[40:41], v[136:137], v[214:215]
	v_pk_fma_f32 v[46:47], v[46:47], v[142:143], v[212:213]
	v_cvt_pk_bf16_f32 v40, v44, v45
	s_nop 0
	v_cvt_pk_bf16_f32 v41, v46, v47
	v_cvt_pk_bf16_f32 v42, v42, v43
	v_cvt_pk_bf16_f32 v43, v48, v49
	global_store_dwordx4 v[56:57], v[40:43], off
	s_nop 0
	s_nop 0
	s_nop 0
	v_lshl_add_u64 v[48:49], v[160:161], 0, s[22:23]
	v_lshl_add_u64 v[50:51], v[48:49], 2, s[6:7]
	s_waitcnt vmcnt(14)
	v_pk_fma_f32 v[36:37], v[36:37], v[132:133], v[218:219]
	s_waitcnt vmcnt(14)
	v_pk_fma_f32 v[40:41], v[34:35], v[130:131], v[224:225]
	v_pk_fma_f32 v[34:35], v[32:33], v[128:129], v[222:223]
	v_pk_fma_f32 v[38:39], v[38:39], v[134:135], v[220:221]
	v_cvt_pk_bf16_f32 v32, v36, v37
	s_nop 0
	v_cvt_pk_bf16_f32 v33, v38, v39
	v_cvt_pk_bf16_f32 v34, v34, v35
	v_cvt_pk_bf16_f32 v35, v40, v41
	global_store_dwordx4 v[56:57], v[32:35], off offset:256
	s_nop 0
	s_nop 0
	s_nop 0
	v_lshl_add_u64 v[40:41], v[48:49], 1, s[28:29]
	s_waitcnt vmcnt(12)
	v_pk_fma_f32 v[28:29], v[28:29], v[140:141], v[226:227]
	s_waitcnt vmcnt(12)
	v_pk_fma_f32 v[32:33], v[26:27], v[138:139], v[232:233]
	v_pk_fma_f32 v[26:27], v[24:25], v[136:137], v[230:231]
	v_pk_fma_f32 v[30:31], v[30:31], v[142:143], v[228:229]
	v_cvt_pk_bf16_f32 v24, v28, v29
	s_nop 0
	v_cvt_pk_bf16_f32 v25, v30, v31
	v_cvt_pk_bf16_f32 v26, v26, v27
	v_cvt_pk_bf16_f32 v27, v32, v33
	global_store_dwordx4 v[40:41], v[24:27], off
	s_nop 0
	s_nop 0
	s_nop 0
	v_lshl_add_u64 v[32:33], v[160:161], 0, s[24:25]
	v_lshl_add_u64 v[34:35], v[32:33], 2, s[6:7]
	s_waitcnt vmcnt(10)
	v_pk_fma_f32 v[20:21], v[20:21], v[132:133], v[234:235]
	s_waitcnt vmcnt(10)
	v_pk_fma_f32 v[24:25], v[18:19], v[130:131], v[240:241]
	v_pk_fma_f32 v[18:19], v[16:17], v[128:129], v[238:239]
	v_pk_fma_f32 v[22:23], v[22:23], v[134:135], v[236:237]
	v_cvt_pk_bf16_f32 v16, v20, v21
	s_nop 0
	v_cvt_pk_bf16_f32 v17, v22, v23
	v_cvt_pk_bf16_f32 v18, v18, v19
	v_cvt_pk_bf16_f32 v19, v24, v25
	global_store_dwordx4 v[40:41], v[16:19], off offset:256
	s_nop 0
	s_nop 0
	s_nop 0
	v_lshl_add_u64 v[24:25], v[32:33], 1, s[28:29]
	s_waitcnt vmcnt(8)
	v_pk_fma_f32 v[12:13], v[12:13], v[140:141], v[186:187]
	s_waitcnt vmcnt(8)
	v_pk_fma_f32 v[16:17], v[10:11], v[138:139], v[192:193]
	v_pk_fma_f32 v[10:11], v[8:9], v[136:137], v[190:191]
	v_pk_fma_f32 v[14:15], v[14:15], v[142:143], v[188:189]
	v_cvt_pk_bf16_f32 v8, v12, v13
	s_nop 0
	v_cvt_pk_bf16_f32 v9, v14, v15
	v_cvt_pk_bf16_f32 v10, v10, v11
	v_cvt_pk_bf16_f32 v11, v16, v17
	global_store_dwordx4 v[24:25], v[8:11], off
	s_nop 0
	s_nop 0
	s_nop 0
	s_waitcnt vmcnt(6)
	v_pk_fma_f32 v[4:5], v[4:5], v[132:133], v[194:195]
	s_waitcnt vmcnt(6)
	v_pk_fma_f32 v[8:9], v[2:3], v[130:131], v[200:201]
	v_pk_fma_f32 v[2:3], v[0:1], v[128:129], v[198:199]
	v_pk_fma_f32 v[6:7], v[6:7], v[134:135], v[196:197]
	v_cvt_pk_bf16_f32 v0, v4, v5
	s_nop 0
	v_cvt_pk_bf16_f32 v1, v6, v7
	v_cvt_pk_bf16_f32 v2, v2, v3
	v_cvt_pk_bf16_f32 v3, v8, v9
	global_store_dwordx4 v[24:25], v[0:3], off offset:256
	s_cbranch_vccnz .LBB0_736
	s_andn2_b64 vcc, exec, s[10:11]
	s_cbranch_vccnz .LBB0_735
	s_barrier
	s_branch .LBB0_735
